# v92 plus MLA attention: eight scalar tail instructions (next slot, row counters, slot rotation) moved into the MFMA->VALU wait behind the last QK MFMA
# speedup vs baseline: 1.0097x; 1.0030x over previous
.Latt_mla_dmaend:
	s_waitcnt lgkmcnt(3)
	v_mfma_f32_32x32x16_bf16 v[64:79], v[112:115], v[130:133], v[96:111]
	ds_read_b128 v[112:115], v209 offset:160
	v_mfma_f32_32x32x16_bf16 v[64:79], v[116:119], v[134:137], v[64:79]
	ds_read_b128 v[116:119], v209 offset:192
	s_waitcnt lgkmcnt(3)
	v_mfma_f32_32x32x16_bf16 v[64:79], v[120:123], v[138:141], v[64:79]
	ds_read_b128 v[120:123], v209 offset:224
	v_mfma_f32_32x32x16_bf16 v[64:79], v[124:127], v[142:145], v[64:79]
	ds_read_b128 v[124:127], v209 offset:256
	s_waitcnt lgkmcnt(3)
	v_mfma_f32_32x32x16_bf16 v[64:79], v[250:253], v[146:149], v[64:79]
	ds_read_b128 v[250:253], v209 offset:288
	v_mfma_f32_32x32x16_bf16 v[64:79], v[112:115], v[150:153], v[64:79]
	ds_read_b128 v[112:115], v209 offset:320
	s_waitcnt lgkmcnt(3)
	v_mfma_f32_32x32x16_bf16 v[64:79], v[116:119], v[154:157], v[64:79]
	ds_read_b128 v[116:119], v209 offset:352
	v_mfma_f32_32x32x16_bf16 v[64:79], v[120:123], v[158:161], v[64:79]
	ds_read_b128 v[120:123], v209 offset:12800
	s_waitcnt lgkmcnt(3)
	v_mfma_f32_32x32x16_bf16 v[64:79], v[124:127], v[162:165], v[64:79]
	ds_read_b128 v[124:127], v209 offset:12832
	v_mfma_f32_32x32x16_bf16 v[64:79], v[250:253], v[166:169], v[64:79]
	ds_read_b128 v[250:253], v209 offset:12864
	s_waitcnt lgkmcnt(3)
	v_mfma_f32_32x32x16_bf16 v[64:79], v[112:115], v[170:173], v[64:79]
	ds_read_b128 v[112:115], v209 offset:12896
	v_mfma_f32_32x32x16_bf16 v[64:79], v[116:119], v[174:177], v[64:79]
	ds_read_b128 v[116:119], v209 offset:12928
	s_waitcnt lgkmcnt(3)
	v_mfma_f32_32x32x16_bf16 v[80:95], v[120:123], v[130:133], v[96:111]
	ds_read_b128 v[120:123], v209 offset:12960
	v_mfma_f32_32x32x16_bf16 v[80:95], v[124:127], v[134:137], v[80:95]
	ds_read_b128 v[124:127], v209 offset:12992
	s_waitcnt lgkmcnt(3)
	v_mfma_f32_32x32x16_bf16 v[80:95], v[250:253], v[138:141], v[80:95]
	ds_read_b128 v[250:253], v209 offset:13024
	v_mfma_f32_32x32x16_bf16 v[80:95], v[112:115], v[142:145], v[80:95]
	ds_read_b128 v[112:115], v209 offset:13056
	s_waitcnt lgkmcnt(3)
	v_mfma_f32_32x32x16_bf16 v[80:95], v[116:119], v[146:149], v[80:95]
	ds_read_b128 v[116:119], v209 offset:13088
	v_max3_f32 v211, v64, v65, v66
	v_mfma_f32_32x32x16_bf16 v[80:95], v[120:123], v[150:153], v[80:95]
	ds_read_b128 v[120:123], v209 offset:13120
	v_max3_f32 v213, v67, v68, v69
	s_waitcnt lgkmcnt(3)
	v_mfma_f32_32x32x16_bf16 v[80:95], v[124:127], v[154:157], v[80:95]
	ds_read_b128 v[124:127], v209 offset:13152
	v_max3_f32 v211, v211, v70, v71
	v_mfma_f32_32x32x16_bf16 v[80:95], v[250:253], v[158:161], v[80:95]
	v_max3_f32 v213, v213, v72, v73
	s_waitcnt lgkmcnt(2)
	v_mfma_f32_32x32x16_bf16 v[80:95], v[112:115], v[162:165], v[80:95]
	v_max3_f32 v211, v211, v74, v75
	v_mfma_f32_32x32x16_bf16 v[80:95], v[116:119], v[166:169], v[80:95]
	v_max3_f32 v213, v213, v76, v77
	s_waitcnt lgkmcnt(0)
	v_mfma_f32_32x32x16_bf16 v[80:95], v[120:123], v[170:173], v[80:95]
	v_max3_f32 v211, v211, v78, v79
	v_mfma_f32_32x32x16_bf16 v[80:95], v[124:127], v[174:177], v[80:95]
	ds_read_b128 v[112:115], v219 offset:0
	ds_read_b128 v[116:119], v219 offset:4608
	ds_read_b128 v[120:123], v219 offset:9216
	s_add_i32 s30, s52, 1
	s_cmp_lg_u32 s52, 2
	s_cselect_b32 s57, s30, 0
	s_add_i32 s49, s49, 64
	s_add_i32 s51, s51, 64
	s_mov_b32 s56, s53
	s_mov_b32 s53, s52
	s_mov_b32 s52, s57
	s_nop 0
	v_max3_f32 v215, v80, v81, v82
	v_max3_f32 v209, v83, v84, v85
	v_max3_f32 v215, v215, v86, v87
	v_max3_f32 v209, v209, v88, v89
	v_max3_f32 v215, v215, v90, v91
	v_max3_f32 v209, v209, v92, v93
	v_max3_f32 v215, v215, v94, v95
	v_max3_f32 v209, v209, v211, v213
	v_max_f32_e32 v209, v209, v215
	v_cmp_lt_f32_e32 vcc, s58, v209
	s_cbranch_vccnz .Latt_mla_rare

.Latt_mla_wd:
	s_add_i32 s55, s55, 1
	s_mul_i32 s30, s56, 0x6400
	v_add_u32_e32 v209, s30, v246
	s_mul_i32 s30, s56, 0x4800
	v_add_u32_e32 v219, s30, v247
	s_cmp_eq_u32 s20, s55
	s_barrier
	s_cbranch_scc0 .LBB0_178
	s_branch .LBB0_153
